# HGRN pass 3: RMS-norm weight vectors loaded once per phase instead of twice per 64-token sub-chunk (removes an exposed L2 round trip from the serial tail of each sub-chunk)
# baseline (speedup 1.0000x reference)
; #define LAS __attribute__((address_space(3)))
; template <bool OUT> DI void hgrn_item(LAS unsigned char* lds, bf16_t* proj, float* hst, float* hdv, const float* normw, int item, bool dry) {
;     const int tid = threadIdx.x, lane = tid & 63, w = __builtin_amdgcn_readfirstlane(tid >> 6);
;     const int b = item >> 6, h = (item >> 4) & 3, c = item & 15;
;     const int d = tid & 127, tq = tid >> 7;
;     LAS bf16_t* Qt = (LAS bf16_t*)(lds + HQ_OFF); LAS bf16_t* Kt = (LAS bf16_t*)(lds + HK_OFF); LAS bf16_t* KtT = (LAS bf16_t*)(lds + HKT_OFF);
;     LAS bf16_t* VT = (LAS bf16_t*)(lds + HVT_OFF); LAS bf16_t* Ab = (LAS bf16_t*)(lds + HA_OFF);
;     LAS float* Dv = (LAS float*)(lds + HD_OFF); LAS float* bpart = (LAS float*)(lds + HBP_OFF); LAS float* ssq = (LAS float*)(lds + HSS_OFF); LAS float* rsd = (LAS float*)(lds + HRS_OFF);
;     const int e16 = lane & 15, rq = lane >> 4;
;     f32x4 st[8];
;     float* hs = hst + (size_t)item * 16384 + (size_t)(w * 8) * 256 + lane * 4;
;     if (OUT) {
; #pragma unroll
;         for (int i = 0; i < 8; ++i) st[i] = *(const f32x4*)(hs + i * 256);
;     } else {
; #pragma unroll
;         for (int i = 0; i < 8; ++i) st[i] = (f32x4){0.f, 0.f, 0.f, 0.f};
;     }
;     float btot = 0.f;
;     unsigned rg[8], rqv[8], rvv[8];
;     ...
;     HG_LOAD(0);
; #pragma unroll 1
;     for (int sc = 0; sc < 4; ++sc) {
;         const size_t row0 = (size_t)b * 4096 + c * 256 + sc * 64;
;     ...
;                 const f32x4 n0 = *(const f32x4*)(normw + e0), n1 = *(const f32x4*)(normw + e0 + 4); const u32x4 g = gate8[j];
.LBB0_1165:
	s_cmp_lt_i32 s90, 6
	s_cselect_b64 s[6:7], -1, 0
	s_and_b64 s[12:13], s[6:7], s[4:5]
	s_andn2_b64 vcc, exec, s[12:13]
	s_cbranch_vccnz .LBB0_1179
	s_cmpk_gt_i32 s2, 0x1ff
	s_movk_i32 s10, 0x1ff
	s_cbranch_scc1 .LBB0_1179
	v_and_b32_e32 v2, 0x7f, v183
	v_lshrrev_b32_e32 v3, 3, v183
	v_and_b32_e32 v76, 0x70, v3
	v_mul_u32_u24_e32 v5, 0x48, v2
	v_lshrrev_b32_e32 v3, 4, v182
	v_lshlrev_b32_e32 v5, 1, v5
	v_lshlrev_b32_e32 v6, 1, v76
	v_and_b32_e32 v8, 48, v182
	v_and_b32_e32 v1, 15, v183
	v_add3_u32 v77, 0, v5, v6
	v_and_b32_e32 v6, 48, v183
	v_lshlrev_b32_e32 v7, 3, v3
	v_add_u32_e32 v105, 0, v8
	s_add_i32 s33, 0, 0x11800
	v_add_u32_e32 v93, 0, v6
	v_lshlrev_b32_e32 v104, 2, v3
	v_sub_u32_e32 v8, v105, v7
	v_add_u32_e32 v9, s33, v6
	v_lshlrev_b32_e32 v6, 2, v1
	s_add_i32 s14, 0, 0x14f00
	v_lshlrev_b32_e32 v7, 5, v183
	v_mul_u32_u24_e32 v3, 0x840, v3
	v_and_b32_e32 v74, 0x1e0, v7
	v_mul_u32_u24_e32 v7, 0x88, v76
	v_add3_u32 v109, s14, v6, v3
	v_mbcnt_lo_u32_b32 v6, -1, 0
	v_or_b32_e32 v7, v7, v2
	v_mbcnt_hi_u32_b32 v6, -1, v6
	v_lshl_add_u32 v107, v7, 1, 0
	v_add_u32_e32 v7, 0x200, v183
	v_and_b32_e32 v12, 64, v6
	v_lshrrev_b32_e32 v82, 4, v7
	v_xor_b32_e32 v7, 1, v6
	v_add_u32_e32 v12, 64, v12
	v_cmp_lt_i32_e32 vcc, v7, v12
	s_load_dwordx2 s[6:7], s[0:1], 0x80
	v_mov_b32_e32 v75, 0
	v_cndmask_b32_e32 v7, v6, v7, vcc
	v_lshlrev_b32_e32 v110, 2, v7
	v_xor_b32_e32 v7, 2, v6
	v_cmp_lt_i32_e32 vcc, v7, v12
	s_add_i32 s4, 0, 0x13e00
	v_lshlrev_b32_e32 v5, 2, v2
	v_cndmask_b32_e32 v7, v6, v7, vcc
	v_lshlrev_b32_e32 v111, 2, v7
	v_xor_b32_e32 v7, 4, v6
	v_cmp_lt_i32_e32 vcc, v7, v12
	s_waitcnt lgkmcnt(0)
	v_lshl_add_u64 v[78:79], s[6:7], 0, v[74:75]
	global_load_dwordx4 v[232:235], v[78:79], off
	global_load_dwordx4 v[236:239], v[78:79], off offset:16
	s_add_i32 s6, 0, 0x13c00
	v_cndmask_b32_e32 v7, v6, v7, vcc
	v_lshlrev_b32_e32 v112, 2, v7
	v_xor_b32_e32 v7, 8, v6
	v_cmp_lt_i32_e32 vcc, v7, v12
	v_lshrrev_b32_e32 v80, 4, v183
	v_lshlrev_b32_e32 v4, 2, v182
	v_cndmask_b32_e32 v6, v6, v7, vcc
	v_lshlrev_b32_e32 v113, 2, v6
	v_lshrrev_b32_e32 v6, 7, v183
	v_mul_hi_u32_u24_e32 v7, 0x32000, v6
	v_mul_u32_u24_e32 v6, 0x32000, v6
	v_lshl_add_u32 v81, v183, 2, s4
	v_add_u32_e32 v83, s4, v5
	s_movk_i32 s4, 0x80
	v_add_u32_e32 v10, s14, v74
	v_add_u32_e32 v106, s6, v5
	v_mul_u32_u24_e32 v5, 0x210, v80
	s_movk_i32 s6, 0xff
	s_movk_i32 s8, 0x17f
	v_mul_u32_u24_e32 v11, 0x110, v1
	v_mul_u32_u24_e32 v108, 0x90, v1
	v_mul_u32_u24_e32 v3, 0x210, v82
	v_lshl_or_b32 v6, v2, 1, v6
	v_lshlrev_b32_e32 v74, 4, v1
	s_mov_b32 s15, 0
	v_cmp_gt_u32_e64 s[4:5], s4, v183
	v_cmp_lt_u32_e64 s[6:7], s6, v183
	v_cmp_lt_u32_e64 s[8:9], s8, v183
	v_cmp_lt_u32_e64 s[10:11], s10, v183
	s_movk_i32 s38, 0x110
	s_movk_i32 s39, 0x90
	v_lshl_add_u64 v[84:85], s[48:49], 0, v[6:7]
	s_lshl_b32 s40, s2, 8
	s_lshl_b32 s41, s56, 8
	v_lshl_add_u64 v[86:87], s[48:49], 0, v[74:75]
	v_lshlrev_b32_e32 v74, 2, v4
	s_movk_i32 s47, 0x1000
	s_movk_i32 s50, 0x3200
	v_lshlrev_b32_e32 v88, 1, v2
	s_movk_i32 s51, 0x3000
	s_movk_i32 s52, 0x4000
	s_movk_i32 s53, 0x6000
	s_mov_b32 s54, 0xa000
	s_movk_i32 s55, 0x7000
	s_mov_b32 s58, 0x9000
	s_mov_b32 s59, 0xd000
	s_mov_b32 s66, 0x10000
	s_mov_b32 s67, 0xc000
	s_mov_b32 s68, 0x13000
	s_mov_b32 s69, 0x16000
	s_mov_b32 s72, 0x19000
	s_mov_b32 s73, 0x1c000
	s_mov_b32 s74, 0x1d000
	s_mov_b32 s75, 0x1f000
	s_mov_b32 s76, 0x23000
	s_mov_b32 s77, 0x20000
	s_mov_b32 s78, 0x22000
	s_mov_b32 s79, 0x26000
	s_mov_b32 s80, 0x29000
	s_mov_b32 s81, 0x25000
	s_mov_b32 s82, 0x2c000
	s_mov_b32 s84, 0x2f000
	v_mov_b32_e32 v114, 0x3200
	v_add_u32_e32 v115, v8, v11
	v_add_u32_e32 v116, v9, v108
	v_add_u32_e32 v117, v10, v5
	v_mov_b32_e32 v118, 0x358637bd
	v_add_u32_e32 v119, v10, v3
	v_mov_b64_e32 v[90:91], s[48:49]
	v_mov_b32_e32 v89, v75
	s_mov_b32 s16, s2
	s_branch .LBB0_1169

; #define LAS __attribute__((address_space(3)))
; DI unsigned pk2(float lo, float hi) { f32x2 v = {lo, hi}; bfv2 b = __builtin_convertvector(v, bfv2); return __builtin_bit_cast(unsigned, b); }
; DI bf16_t f2bf(float x) { return (bf16_t)(pk2(x, 0.f) & 0xffffu); }
; #define MFMA16(a, b, c) __builtin_amdgcn_mfma_f32_16x16x32_bf16((a), (b), (c), 0, 0, 0)
; template <bool OUT> DI void hgrn_item(LAS unsigned char* lds, bf16_t* proj, float* hst, float* hdv, const float* normw, int item, bool dry) {
;     ...
;                 for (int r = 0; r < 4; ++r) { const int tt = 16 * ti + 4 * rq + r, ss = 16 * sj + e16; Ab[tt * TP + ss] = (sj <= ti && ss <= tt) ? f2bf(a[r]) : (bf16_t)0; }
;             }
; #pragma unroll
;             for (int ti = 0; ti < 4; ++ti) { o[ti] = (f32x4){0.f, 0.f, 0.f, 0.f};
; #pragma unroll
;                 for (int ks = 0; ks < 4; ++ks) { const LAS bf16_t* qp = Qt + (16 * ti + e16) * QP + 32 * ks + 4 * rq; const u32x2 q0 = *(const LAS u32x2*)qp, q1 = *(const LAS u32x2*)(qp + 16);
;                     u32x4 qa = {q0.x, q0.y, q1.x, q1.y};
;                     u32x4 sb; sb.x = pk2(st[2 * ks][0], st[2 * ks][1]); sb.y = pk2(st[2 * ks][2], st[2 * ks][3]); sb.z = pk2(st[2 * ks + 1][0], st[2 * ks + 1][1]); sb.w = pk2(st[2 * ks + 1][2], st[2 * ks + 1][3]);
;                     o[ti] = MFMA16(__builtin_bit_cast(bf16x8, qa), __builtin_bit_cast(bf16x8, sb), o[ti]); } }
;         }
; #pragma unroll
;         for (int dt = 0; dt < 8; ++dt) {
; #pragma unroll
;             for (int ks = 0; ks < 2; ++ks) { const bf16x8 ka = *(const LAS bf16x8*)(KtT + (16 * dt + e16) * TP + 32 * ks + 8 * rq); st[dt] = MFMA16(ka, vfr[ks], st[dt]); }
;             const f32x4 dv = *(const LAS f32x4*)(Dv + 16 * dt + 4 * rq);
;             st[dt] *= dv;
.LBB0_1170:
	v_or_b32_e32 v56, s14, v104
	v_cmp_gt_u32_e32 vcc, v120, v56
	s_or_b64 s[36:37], s[20:21], vcc
	s_nop 3
	v_cvt_pk_bf16_f32 v50, v50, s0
	v_cndmask_b32_e64 v50, v50, 0, s[36:37]
	v_mad_u64_u32 v[54:55], s[36:37], v56, s39, v[92:93]
	ds_write_b16 v54, v50
	v_or_b32_e32 v50, 1, v56
	v_cmp_gt_u32_e32 vcc, v120, v50
	s_or_b64 s[36:37], s[20:21], vcc
	v_cvt_pk_bf16_f32 v50, v51, s0
	v_cndmask_b32_e64 v50, v50, 0, s[36:37]
	ds_write_b16 v54, v50 offset:144
	v_or_b32_e32 v50, 2, v56
	v_cmp_gt_u32_e32 vcc, v120, v50
	s_or_b64 s[36:37], s[20:21], vcc
	v_cvt_pk_bf16_f32 v50, v52, s0
	v_cndmask_b32_e64 v50, v50, 0, s[36:37]
	ds_write_b16 v54, v50 offset:288
	v_or_b32_e32 v50, 3, v56
	v_cmp_gt_u32_e32 vcc, v120, v50
	s_or_b64 s[36:37], s[20:21], vcc
	v_cvt_pk_bf16_f32 v50, v53, s0
	v_cndmask_b32_e64 v50, v50, 0, s[36:37]
	ds_write_b16 v54, v50 offset:432
	ds_read2_b64 v[50:53], v115 offset1:4
	ds_read2_b64 v[54:57], v115 offset0:8 offset1:12
	s_waitcnt vmcnt(7)
	v_cvt_pk_bf16_f32 v66, v6, v7
	v_cvt_pk_bf16_f32 v67, v8, v9
	s_waitcnt vmcnt(6)
	v_cvt_pk_bf16_f32 v68, v10, v11
	v_cvt_pk_bf16_f32 v69, v12, v13
	s_waitcnt vmcnt(5)
	v_cvt_pk_bf16_f32 v70, v2, v3
	v_cvt_pk_bf16_f32 v71, v4, v5
	s_waitcnt lgkmcnt(1)
	v_mfma_f32_16x16x32_bf16 v[50:53], v[50:53], v[66:69], 0
	s_waitcnt vmcnt(4)
	v_cvt_pk_bf16_f32 v72, v18, v19
	v_cvt_pk_bf16_f32 v73, v20, v21
	s_waitcnt vmcnt(3)
	v_cvt_pk_bf16_f32 v100, v14, v15
	v_cvt_pk_bf16_f32 v101, v16, v17
	s_waitcnt lgkmcnt(0)
	v_mfma_f32_16x16x32_bf16 v[50:53], v[54:57], v[70:73], v[50:53]
	ds_read2_b64 v[54:57], v115 offset0:16 offset1:20
	s_waitcnt vmcnt(2)
	v_cvt_pk_bf16_f32 v102, v26, v27
	v_cvt_pk_bf16_f32 v103, v28, v29
	s_waitcnt vmcnt(1)
	v_cvt_pk_bf16_f32 v144, v22, v23
	v_cvt_pk_bf16_f32 v145, v24, v25
	s_waitcnt lgkmcnt(0)
	v_mfma_f32_16x16x32_bf16 v[50:53], v[54:57], v[100:103], v[50:53]
	ds_read2_b64 v[54:57], v115 offset0:24 offset1:28
	s_waitcnt vmcnt(0)
	v_cvt_pk_bf16_f32 v146, v30, v31
	v_cvt_pk_bf16_f32 v147, v32, v33
	v_add_u32_e32 v62, 0x1000, v115
	ds_read2_b64 v[58:61], v62 offset0:40 offset1:44
	s_waitcnt lgkmcnt(1)
	v_mfma_f32_16x16x32_bf16 v[54:57], v[54:57], v[144:147], v[50:53]
	s_nop 2
	ds_read2_b64 v[50:53], v62 offset0:32 offset1:36
	v_add_u32_e32 v143, 0x2000, v115
	s_waitcnt lgkmcnt(0)
	v_mfma_f32_16x16x32_bf16 v[50:53], v[50:53], v[66:69], 0
	v_mfma_f32_16x16x32_bf16 v[50:53], v[58:61], v[70:73], v[50:53]
	ds_read2_b64 v[58:61], v62 offset0:48 offset1:52
	s_waitcnt lgkmcnt(0)
	v_mfma_f32_16x16x32_bf16 v[50:53], v[58:61], v[100:103], v[50:53]
	ds_read2_b64 v[58:61], v62 offset0:56 offset1:60
	ds_read2_b64 v[62:65], v143 offset0:72 offset1:76
	s_waitcnt lgkmcnt(1)
	v_mfma_f32_16x16x32_bf16 v[58:61], v[58:61], v[144:147], v[50:53]
	s_nop 3
	ds_read2_b64 v[50:53], v143 offset0:64 offset1:68
	s_waitcnt lgkmcnt(0)
	v_mfma_f32_16x16x32_bf16 v[50:53], v[50:53], v[66:69], 0
	v_mfma_f32_16x16x32_bf16 v[50:53], v[62:65], v[70:73], v[50:53]
	ds_read2_b64 v[62:65], v143 offset0:80 offset1:84
	s_waitcnt lgkmcnt(0)
	v_mfma_f32_16x16x32_bf16 v[50:53], v[62:65], v[100:103], v[50:53]
	ds_read2_b64 v[62:65], v143 offset0:88 offset1:92
	v_add_u32_e32 v143, 0x3000, v115
	s_waitcnt lgkmcnt(0)
	v_mfma_f32_16x16x32_bf16 v[62:65], v[62:65], v[144:147], v[50:53]
	s_nop 3
	ds_read2_b64 v[50:53], v143 offset0:96 offset1:100
	s_waitcnt lgkmcnt(0)
	v_mfma_f32_16x16x32_bf16 v[50:53], v[50:53], v[66:69], 0
	ds_read2_b64 v[66:69], v143 offset0:104 offset1:108
	s_waitcnt lgkmcnt(0)
	v_mfma_f32_16x16x32_bf16 v[50:53], v[66:69], v[70:73], v[50:53]
	ds_read2_b64 v[66:69], v143 offset0:112 offset1:116
	s_waitcnt lgkmcnt(0)
	v_mfma_f32_16x16x32_bf16 v[50:53], v[66:69], v[100:103], v[50:53]
	ds_read2_b64 v[66:69], v143 offset0:120 offset1:124
	v_lshl_add_u64 v[102:103], v[98:99], 0, s[34:35]
	v_lshl_add_u64 v[100:101], v[96:97], 0, s[34:35]
	s_waitcnt lgkmcnt(0)
	v_mfma_f32_16x16x32_bf16 v[70:73], v[66:69], v[144:147], v[50:53]
	v_add_u32_e32 v66, v93, v108
	s_nop 1
	ds_read_b128 v[50:53], v66 offset:34816
	v_add_u32_e32 v67, 0x13c00, v93
	s_waitcnt lgkmcnt(0)
	v_mfma_f32_16x16x32_bf16 v[6:9], v[50:53], v[46:49], v[6:9]
	ds_read_b128 v[50:53], v66 offset:34880
	s_add_u32 s34, s34, 0xc8000
	s_addc_u32 s35, s35, 0
	s_waitcnt lgkmcnt(0)
	v_mfma_f32_16x16x32_bf16 v[6:9], v[50:53], v[42:45], v[6:9]
	ds_read_b128 v[50:53], v67
	s_cmp_lg_u32 s34, 0x320000
	s_waitcnt lgkmcnt(0)
	s_nop 4
	v_pk_mul_f32 v[8:9], v[8:9], v[52:53]
	v_pk_mul_f32 v[6:7], v[6:7], v[50:51]
	ds_read_b128 v[50:53], v66 offset:37120
	s_waitcnt lgkmcnt(0)
	v_mfma_f32_16x16x32_bf16 v[10:13], v[50:53], v[46:49], v[10:13]
	ds_read_b128 v[50:53], v66 offset:37184
	s_waitcnt lgkmcnt(0)
	v_mfma_f32_16x16x32_bf16 v[10:13], v[50:53], v[42:45], v[10:13]
	ds_read_b128 v[50:53], v67 offset:64
	s_waitcnt lgkmcnt(0)
	s_nop 5
	v_pk_mul_f32 v[12:13], v[12:13], v[52:53]
	v_pk_mul_f32 v[10:11], v[10:11], v[50:51]
	ds_read_b128 v[50:53], v66 offset:39424
	s_waitcnt lgkmcnt(0)
	v_mfma_f32_16x16x32_bf16 v[2:5], v[50:53], v[46:49], v[2:5]
	ds_read_b128 v[50:53], v66 offset:39488
	s_waitcnt lgkmcnt(0)
	v_mfma_f32_16x16x32_bf16 v[2:5], v[50:53], v[42:45], v[2:5]
	ds_read_b128 v[50:53], v67 offset:128
	s_waitcnt lgkmcnt(0)
	s_nop 5
	v_pk_mul_f32 v[4:5], v[4:5], v[52:53]
	v_pk_mul_f32 v[2:3], v[2:3], v[50:51]
	ds_read_b128 v[50:53], v66 offset:41728
	s_waitcnt lgkmcnt(0)
	v_mfma_f32_16x16x32_bf16 v[18:21], v[50:53], v[46:49], v[18:21]
	ds_read_b128 v[50:53], v66 offset:41792
	s_waitcnt lgkmcnt(0)
	v_mfma_f32_16x16x32_bf16 v[18:21], v[50:53], v[42:45], v[18:21]
	ds_read_b128 v[50:53], v67 offset:192
	s_waitcnt lgkmcnt(0)
; #define LAS __attribute__((address_space(3)))
; #define MFMA16(a, b, c) __builtin_amdgcn_mfma_f32_16x16x32_bf16((a), (b), (c), 0, 0, 0)
; template <bool OUT> DI void hgrn_item(LAS unsigned char* lds, bf16_t* proj, float* hst, float* hdv, const float* normw, int item, bool dry) {
;     ...
;         for (int dt = 0; dt < 8; ++dt) {
; #pragma unroll
;             for (int ks = 0; ks < 2; ++ks) { const bf16x8 ka = *(const LAS bf16x8*)(KtT + (16 * dt + e16) * TP + 32 * ks + 8 * rq); st[dt] = MFMA16(ka, vfr[ks], st[dt]); }
;             const f32x4 dv = *(const LAS f32x4*)(Dv + 16 * dt + 4 * rq);
;             st[dt] *= dv;
;         }
;         u32x4 gate8[2];
;         if (OUT) {
; #pragma unroll
;             for (int j = 0; j < 2; ++j) { const int cch = tid + 512 * j; gate8[j] = *(const u32x4*)(proj + (row0 + (cch >> 4)) * NPJ + C_HG + h * 128 + 8 * (cch & 15)); }
;         }
;         __syncthreads();
;         if (OUT) {
; #pragma unroll
;             for (int ti = 0; ti < 4; ++ti)
; #pragma unroll
;                 for (int ks = 0; ks < 2; ++ks) if (2 * ks <= ti) { const bf16x8 aa = *(const LAS bf16x8*)(Ab + (16 * ti + e16) * TP + 32 * ks + 8 * rq); o[ti] = MFMA16(aa, vfr[ks], o[ti]); }
;             LAS float* Ob = (LAS float*)(lds + HOB_OFF);
; #pragma unroll
;             for (int ti = 0; ti < 4; ++ti)
; #pragma unroll
;                 for (int r = 0; r < 4; ++r) Ob[(16 * ti + 4 * rq + r) * OBP + w * 16 + e16] = o[ti][r];
;             __syncthreads();
	s_nop 5
	v_pk_mul_f32 v[20:21], v[20:21], v[52:53]
	v_pk_mul_f32 v[18:19], v[18:19], v[50:51]
	ds_read_b128 v[50:53], v66 offset:44032
	s_waitcnt lgkmcnt(0)
	v_mfma_f32_16x16x32_bf16 v[14:17], v[50:53], v[46:49], v[14:17]
	ds_read_b128 v[50:53], v66 offset:44096
	s_waitcnt lgkmcnt(0)
	v_mfma_f32_16x16x32_bf16 v[14:17], v[50:53], v[42:45], v[14:17]
	ds_read_b128 v[50:53], v67 offset:256
	s_waitcnt lgkmcnt(0)
	s_nop 5
	v_pk_mul_f32 v[16:17], v[16:17], v[52:53]
	v_pk_mul_f32 v[14:15], v[14:15], v[50:51]
	ds_read_b128 v[50:53], v66 offset:46336
	s_waitcnt lgkmcnt(0)
	v_mfma_f32_16x16x32_bf16 v[26:29], v[50:53], v[46:49], v[26:29]
	ds_read_b128 v[50:53], v66 offset:46400
	s_waitcnt lgkmcnt(0)
	v_mfma_f32_16x16x32_bf16 v[26:29], v[50:53], v[42:45], v[26:29]
	ds_read_b128 v[50:53], v67 offset:320
	s_waitcnt lgkmcnt(0)
	s_nop 5
	v_pk_mul_f32 v[28:29], v[28:29], v[52:53]
	v_pk_mul_f32 v[26:27], v[26:27], v[50:51]
	ds_read_b128 v[50:53], v66 offset:48640
	s_waitcnt lgkmcnt(0)
	v_mfma_f32_16x16x32_bf16 v[22:25], v[50:53], v[46:49], v[22:25]
	ds_read_b128 v[50:53], v66 offset:48704
	s_waitcnt lgkmcnt(0)
	v_mfma_f32_16x16x32_bf16 v[22:25], v[50:53], v[42:45], v[22:25]
	ds_read_b128 v[50:53], v67 offset:384
	s_waitcnt lgkmcnt(0)
	s_nop 5
	v_pk_mul_f32 v[24:25], v[24:25], v[52:53]
	v_pk_mul_f32 v[22:23], v[22:23], v[50:51]
	ds_read_b128 v[50:53], v66 offset:50944
	s_waitcnt lgkmcnt(0)
	v_mfma_f32_16x16x32_bf16 v[30:33], v[50:53], v[46:49], v[30:33]
	ds_read_b128 v[50:53], v66 offset:51008
	s_waitcnt lgkmcnt(0)
	v_mfma_f32_16x16x32_bf16 v[30:33], v[50:53], v[42:45], v[30:33]
	ds_read_b128 v[50:53], v67 offset:448
	s_waitcnt lgkmcnt(0)
	s_nop 5
	v_pk_mul_f32 v[30:31], v[30:31], v[50:51]
	v_add_co_u32_e32 v50, vcc, s47, v102
	v_pk_mul_f32 v[32:33], v[32:33], v[52:53]
	s_nop 0
	v_addc_co_u32_e32 v51, vcc, 0, v103, vcc
	global_load_dwordx4 v[66:69], v[50:51], off offset:512
	v_add_co_u32_e32 v50, vcc, s47, v100
	s_nop 1
	v_addc_co_u32_e32 v51, vcc, 0, v101, vcc
	global_load_dwordx4 v[50:53], v[50:51], off offset:512
	s_barrier
	ds_read_b128 v[144:147], v116
	s_waitcnt lgkmcnt(0)
	v_mfma_f32_16x16x32_bf16 v[54:57], v[144:147], v[46:49], v[54:57]
	ds_read_b128 v[144:147], v116 offset:2304
	s_waitcnt lgkmcnt(0)
	v_mfma_f32_16x16x32_bf16 v[58:61], v[144:147], v[46:49], v[58:61]
	ds_read_b128 v[144:147], v116 offset:4608
	s_waitcnt lgkmcnt(0)
	v_mfma_f32_16x16x32_bf16 v[62:65], v[144:147], v[46:49], v[62:65]
	ds_read_b128 v[144:147], v116 offset:4672
	s_waitcnt lgkmcnt(0)
	v_mfma_f32_16x16x32_bf16 v[62:65], v[144:147], v[42:45], v[62:65]
	ds_read_b128 v[144:147], v116 offset:6912
	s_waitcnt lgkmcnt(0)
	v_mfma_f32_16x16x32_bf16 v[46:49], v[144:147], v[46:49], v[70:73]
	s_nop 2
	ds_read_b128 v[70:73], v116 offset:6976
	ds_write2_b32 v125, v54, v55 offset1:132
	s_waitcnt lgkmcnt(1)
	v_mfma_f32_16x16x32_bf16 v[42:45], v[70:73], v[42:45], v[46:49]
	s_nop 2
	v_add_u32_e32 v46, 0x400, v125
	ds_write2_b32 v46, v56, v57 offset0:8 offset1:140
	v_add_u32_e32 v46, 0x2000, v125
	ds_write2_b32 v46, v58, v59 offset0:64 offset1:196
	v_add_u32_e32 v46, 0x2400, v125
	ds_write2_b32 v46, v60, v61 offset0:72 offset1:204
	v_add_u32_e32 v46, 0x4200, v125
	ds_write2_b32 v46, v62, v63 offset1:132
	v_add_u32_e32 v46, 0x4600, v125
	ds_write2_b32 v46, v64, v65 offset0:8 offset1:140
	v_add_u32_e32 v46, 0x6200, v125
	ds_write2_b32 v46, v42, v43 offset0:64 offset1:196
	v_add_u32_e32 v42, 0x6600, v125
	ds_write2_b32 v42, v44, v45 offset0:72 offset1:204
	s_waitcnt lgkmcnt(0)
	s_barrier
; #define LAS __attribute__((address_space(3)))
; DI float bflo(unsigned w) { return __uint_as_float(w << 16); }
; DI float bfhi(unsigned w) { return __uint_as_float(w & 0xffff0000u); }
; DI u32x4 pack8(f32x4 a, f32x4 b) { u32x4 w; w.x = pk2(a[0], a[1]); w.y = pk2(a[2], a[3]); w.z = pk2(b[0], b[1]); w.w = pk2(b[2], b[3]); return w; }
; template <bool OUT> DI void hgrn_item(LAS unsigned char* lds, bf16_t* proj, float* hst, float* hdv, const float* normw, int item, bool dry) {
;     ...
;             for (int j = 0; j < 2; ++j) { const int cch = tid + 512 * j, tt = cch >> 4, e0 = 8 * (cch & 15);
;                 const f32x4 a0 = *(const LAS f32x4*)(Ob + tt * OBP + e0), a1 = *(const LAS f32x4*)(Ob + tt * OBP + e0 + 4);
;                 float q = (a0[0] * a0[0] + a0[1] * a0[1]) + (a0[2] * a0[2] + a0[3] * a0[3]) + (a1[0] * a1[0] + a1[1] * a1[1]) + (a1[2] * a1[2] + a1[3] * a1[3]);
;                 q += __shfl_xor(q, 1); q += __shfl_xor(q, 2); q += __shfl_xor(q, 4); q += __shfl_xor(q, 8);
;                 const float rs = __builtin_amdgcn_rsqf(q * (1.0f / 128.0f) + 1e-6f);
;                 const f32x4 n0 = *(const f32x4*)(normw + e0), n1 = *(const f32x4*)(normw + e0 + 4); const u32x4 g = gate8[j];
;                 f32x4 y0, y1;
;                 y0[0] = a0[0] * rs * n0[0] * bflo(g.x); y0[1] = a0[1] * rs * n0[1] * bfhi(g.x); y0[2] = a0[2] * rs * n0[2] * bflo(g.y); y0[3] = a0[3] * rs * n0[3] * bfhi(g.y);
;                 y1[0] = a1[0] * rs * n1[0] * bflo(g.z); y1[1] = a1[1] * rs * n1[1] * bfhi(g.z); y1[2] = a1[2] * rs * n1[2] * bflo(g.w); y1[3] = a1[3] * rs * n1[3] * bfhi(g.w);
;                 if (!dry) *(u32x4*)(proj + (row0 + tt) * NPJ + C_HQ + h * 128 + e0) = pack8(y0, y1); }
	ds_read_b128 v[42:45], v117
	ds_read_b128 v[46:49], v117 offset:16
	s_waitcnt vmcnt(1)
	v_lshlrev_b32_e32 v64, 16, v68
	v_and_b32_e32 v65, 0xffff0000, v68
	s_waitcnt lgkmcnt(1)
	v_pk_mul_f32 v[54:55], v[44:45], v[44:45]
	v_pk_mul_f32 v[56:57], v[42:43], v[42:43]
	s_nop 0
	v_pk_mov_b32 v[58:59], v[56:57], v[54:55] op_sel:[1,0]
	v_mov_b32_e32 v57, v55
	v_pk_add_f32 v[54:55], v[58:59], v[56:57]
	s_waitcnt lgkmcnt(0)
	v_pk_mul_f32 v[56:57], v[48:49], v[48:49]
	v_pk_mul_f32 v[58:59], v[46:47], v[46:47]
	v_mov_b32_e32 v60, v56
	v_mov_b32_e32 v61, v58
	v_mov_b32_e32 v58, v57
	v_pk_add_f32 v[56:57], v[60:61], v[58:59]
	v_add_f32_e32 v54, v54, v55
	v_add_f32_e32 v54, v54, v57
	v_add_f32_e32 v54, v56, v54
	ds_bpermute_b32 v55, v110, v54
	s_waitcnt lgkmcnt(0)
	v_add_f32_e32 v54, v54, v55
	ds_bpermute_b32 v55, v111, v54
	s_waitcnt lgkmcnt(0)
	v_add_f32_e32 v54, v54, v55
	ds_bpermute_b32 v55, v112, v54
	s_waitcnt lgkmcnt(0)
	v_add_f32_e32 v62, v54, v55
	ds_bpermute_b32 v63, v113, v62
	s_waitcnt lgkmcnt(0)
	v_add_f32_e32 v62, v62, v63
	v_fmamk_f32 v62, v62, 0x3c000000, v118
	v_rsq_f32_e32 v62, v62
	s_nop 0
	v_pk_mul_f32 v[46:47], v[46:47], v[62:63] op_sel_hi:[1,0]
	v_pk_mul_f32 v[48:49], v[48:49], v[62:63] op_sel_hi:[1,0]
	v_pk_mul_f32 v[42:43], v[42:43], v[62:63] op_sel_hi:[1,0]
	v_pk_mul_f32 v[44:45], v[44:45], v[62:63] op_sel_hi:[1,0]
	s_waitcnt vmcnt(0)
	v_pk_mul_f32 v[42:43], v[232:233], v[42:43]
	v_pk_mul_f32 v[46:47], v[236:237], v[46:47]
	v_lshlrev_b32_e32 v58, 16, v69
	v_and_b32_e32 v59, 0xffff0000, v69
	v_pk_mul_f32 v[48:49], v[238:239], v[48:49]
	v_lshlrev_b32_e32 v54, 16, v67
	v_pk_mul_f32 v[48:49], v[48:49], v[58:59]
	v_lshlrev_b32_e32 v58, 16, v66
	v_and_b32_e32 v59, 0xffff0000, v66
	v_and_b32_e32 v55, 0xffff0000, v67
	v_pk_mul_f32 v[44:45], v[234:235], v[44:45]
	v_pk_mul_f32 v[46:47], v[46:47], v[64:65]
	v_pk_mul_f32 v[42:43], v[42:43], v[58:59]
	v_pk_mul_f32 v[44:45], v[44:45], v[54:55]
	v_cvt_pk_bf16_f32 v42, v42, v43
	v_cvt_pk_bf16_f32 v43, v44, v45
	v_cvt_pk_bf16_f32 v44, v46, v47
	v_cvt_pk_bf16_f32 v45, v48, v49
	global_store_dwordx4 v[102:103], v[42:45], off offset:1536
	ds_read_b128 v[42:45], v119
	ds_read_b128 v[46:49], v119 offset:16
	v_lshlrev_b32_e32 v64, 16, v52
	v_and_b32_e32 v65, 0xffff0000, v52
	v_lshlrev_b32_e32 v52, 16, v53
	s_waitcnt lgkmcnt(1)
	v_pk_mul_f32 v[54:55], v[44:45], v[44:45]
	v_pk_mul_f32 v[56:57], v[42:43], v[42:43]
	v_and_b32_e32 v53, 0xffff0000, v53
	v_pk_mov_b32 v[58:59], v[56:57], v[54:55] op_sel:[1,0]
	v_mov_b32_e32 v57, v55
	v_pk_add_f32 v[54:55], v[58:59], v[56:57]
	s_waitcnt lgkmcnt(0)
	v_pk_mul_f32 v[56:57], v[48:49], v[48:49]
	v_pk_mul_f32 v[58:59], v[46:47], v[46:47]
	v_mov_b32_e32 v60, v56
	v_mov_b32_e32 v61, v58
	v_mov_b32_e32 v58, v57
	v_pk_add_f32 v[56:57], v[60:61], v[58:59]
	v_add_f32_e32 v54, v54, v55
	v_add_f32_e32 v54, v54, v57
	v_add_f32_e32 v54, v56, v54
	ds_bpermute_b32 v55, v110, v54
	s_waitcnt lgkmcnt(0)
	v_add_f32_e32 v54, v54, v55
	ds_bpermute_b32 v55, v111, v54
	s_waitcnt lgkmcnt(0)
	v_add_f32_e32 v54, v54, v55
	ds_bpermute_b32 v55, v112, v54
	s_waitcnt lgkmcnt(0)
	v_add_f32_e32 v62, v54, v55
	ds_bpermute_b32 v63, v113, v62
	s_waitcnt lgkmcnt(0)
	v_add_f32_e32 v62, v62, v63
	v_fmamk_f32 v62, v62, 0x3c000000, v118
	v_rsq_f32_e32 v62, v62
	s_nop 0
	v_pk_mul_f32 v[48:49], v[48:49], v[62:63] op_sel_hi:[1,0]
	v_pk_mul_f32 v[46:47], v[46:47], v[62:63] op_sel_hi:[1,0]
	v_pk_mul_f32 v[42:43], v[42:43], v[62:63] op_sel_hi:[1,0]
	v_pk_mul_f32 v[44:45], v[44:45], v[62:63] op_sel_hi:[1,0]
	v_pk_mul_f32 v[42:43], v[232:233], v[42:43]
	v_pk_mul_f32 v[48:49], v[238:239], v[48:49]
	v_pk_mul_f32 v[46:47], v[236:237], v[46:47]
	v_pk_mul_f32 v[48:49], v[48:49], v[52:53]
	v_lshlrev_b32_e32 v52, 16, v50
	v_and_b32_e32 v53, 0xffff0000, v50
	v_lshlrev_b32_e32 v50, 16, v51
	v_and_b32_e32 v51, 0xffff0000, v51
	v_pk_mul_f32 v[44:45], v[234:235], v[44:45]
	v_pk_mul_f32 v[46:47], v[46:47], v[64:65]
	v_pk_mul_f32 v[42:43], v[42:43], v[52:53]
	v_pk_mul_f32 v[44:45], v[44:45], v[50:51]
	v_cvt_pk_bf16_f32 v42, v42, v43
	v_cvt_pk_bf16_f32 v43, v44, v45
	v_cvt_pk_bf16_f32 v44, v46, v47
	v_cvt_pk_bf16_f32 v45, v48, v49
	global_store_dwordx4 v[100:101], v[42:45], off offset:1536
	v_mov_b32_e32 v46, v127
	v_mov_b32_e32 v47, v128
	v_mov_b32_e32 v49, v130
	v_mov_b32_e32 v51, v132
	v_mov_b32_e32 v52, v134
	v_mov_b32_e32 v53, v136
	v_mov_b32_e32 v54, v138
	v_mov_b32_e32 v48, v140
	v_mov_b32_e32 v42, v129
	v_mov_b32_e32 v43, v131
	v_mov_b32_e32 v44, v133
	v_mov_b32_e32 v45, v135
	v_mov_b32_e32 v50, v137
	v_mov_b32_e32 v55, v139
	v_mov_b32_e32 v56, v141
	v_mov_b32_e32 v57, v142
	s_cbranch_scc0 .LBB0_1168
